# attention<false>: dead sequence-end bound computation removed from the tile-0 head
# speedup vs baseline: 1.0019x; 1.0019x over previous
; #define LAS __attribute__((address_space(3)))
; __device__ __forceinline__ unsigned pk2(float lo, float hi) { f32x2_t v = {lo, hi}; bf16x2_t b = __builtin_convertvector(v, bf16x2_t); return __builtin_bit_cast(unsigned, b); }
; template <bool FUSED> __device__ __forceinline__ void attn_phase(const Args& a, LAS unsigned char* lds, int tid, int lane, int wave) {
;     ...
;         const float bsl = __builtin_amdgcn_exp2f(-(float)(slot + 1)) * (float)w.dil * LOG2E;
;         int tl = 4 * h - l31; asm volatile("" : "+v"(tl));
;         const float tlf = (float)tl;
;         const int lo_i = -iq > -64 ? -iq : -64, hi_i = (L - 1 - iq) < 64 ? (L - 1 - iq) : 64;
;         const float rlo = (float)lo_i, rhi = (float)hi_i;
;         const int wq0 = i0 + 32 * wave;
;         const bool edge = (wq0 < 64) || (wq0 + 32 > L - 64);
;         float sum = 0.f;
;         f32x16 o[2]; o[0] = f32x16{}; o[1] = f32x16{};
; #pragma unroll
;         for (int j = 0; j < 5; ++j) {
;             f32x16 st;
; #pragma unroll
;             for (int i = 0; i < 16; ++i) st[i] = -mb;
;             LAS const unsigned char* kp = lds + (32 * wave + 32 * j + l31) * KP + 16 * h;
; #pragma unroll
;             for (int ks = 0; ks < 4; ++ks) { const bf16x8 kf = *(LAS const bf16x8*)(kp + 32 * ks); st = __builtin_amdgcn_mfma_f32_32x32x16_bf16(kf, qf[ks], st, 0, 0, 0); }
;             sum += attn_tile_exp(st, j, tlf, bsl, rlo, rhi);
; #pragma unroll
;             for (int s2 = 0; s2 < 2; ++s2) { u32x4 pw; pw.x = pk2(st[8 * s2 + 0], st[8 * s2 + 1]); pw.y = pk2(st[8 * s2 + 2], st[8 * s2 + 3]); pw.z = pk2(st[8 * s2 + 4], st[8 * s2 + 5]); pw.w = pk2(st[8 * s2 + 6], st[8 * s2 + 7]);
;                 const bf16x8 pf = __builtin_bit_cast(bf16x8, pw);
;                 LAS const unsigned char* vp = lds + LDS_VOFF + (32 * wave + 32 * j + 16 * s2 + 4 * h + q) * VP + 32 * blk + 8 * p;
; #pragma unroll
;                 for (int dt = 0; dt < 2; ++dt) { const s16x4 lo = trrd(vp + dt * 64), hi = trrd(vp + 8 * VP + dt * 64);
;                     const bf16x8 vf = __builtin_shufflevector(lo, hi, 0, 1, 2, 3, 4, 5, 6, 7);
;                     o[dt] = __builtin_amdgcn_mfma_f32_32x32x16_bf16(vf, pf, o[dt], 0, 0, 0); } }
;             __builtin_amdgcn_sched_barrier(0);
;         }
.Lattn1_join:
	v_xor_b32_e32 v0, 0x80000000, v222
	v_mov_b32_e32 v1, v0
	v_mov_b32_e32 v2, v0
	v_mov_b32_e32 v3, v0
	v_mov_b32_e32 v4, v0
	v_mov_b32_e32 v5, v0
	v_mov_b32_e32 v6, v0
	v_mov_b32_e32 v7, v0
	v_mov_b32_e32 v8, v0
	v_mov_b32_e32 v9, v0
	v_mov_b32_e32 v10, v0
	v_mov_b32_e32 v11, v0
	v_mov_b32_e32 v12, v0
	v_mov_b32_e32 v13, v0
	v_mov_b32_e32 v14, v0
	v_mov_b32_e32 v15, v0
	v_exp_f32_e64 v46, -v32
	s_waitcnt lgkmcnt(0)
	v_mfma_f32_32x32x16_bf16 v[16:31], v[38:41], v[88:91], v[0:15]
	ds_read_b128 v[38:41], v199 offset:64
	s_and_b32 s77, s67, 31
	ds_read_b128 v[32:35], v199 offset:96
	s_add_i32 s6, s6, -1
	s_and_b32 s6, s6, s77
	v_mfma_f32_32x32x16_bf16 v[16:31], v[42:45], v[92:95], v[16:31]
	s_lshr_b32 s76, 0x2000, s75
	v_lshl_add_u32 v168, s6, 8, v145
	s_lshl_b32 s6, 1, s75
	v_cvt_f32_u32_e32 v42, s6
	v_cvt_f32_i32_e32 v225, v48
	s_waitcnt lgkmcnt(1)
	v_mfma_f32_32x32x16_bf16 v[16:31], v[38:41], v[100:103], v[16:31]
	v_mul_f32_e32 v36, v46, v42
	v_mul_f32_e32 v224, 0xbfb8aa3b, v36
	s_waitcnt lgkmcnt(0)
	v_mfma_f32_32x32x16_bf16 v[16:31], v[32:35], v[108:111], v[16:31]
	v_readfirstlane_b32 s98, v168
	s_sub_i32 s99, s76, 64
	s_cmp_lt_i32 s98, 64
	s_cbranch_scc1 .Lattn1_skip0
	s_nop 5
	s_nop 1
	v_fma_f32 v16, v224, |v128|, v16
	v_fma_f32 v17, v224, |v129|, v17
	v_exp_f32_e32 v33, v17
	v_fma_f32 v17, v224, |v130|, v18
	v_exp_f32_e32 v34, v17
	v_fma_f32 v17, v224, |v131|, v19
	v_exp_f32_e32 v35, v17
	v_fma_f32 v17, v224, |v132|, v20
	v_exp_f32_e32 v36, v17
	v_fma_f32 v17, v224, |v133|, v21
	v_exp_f32_e32 v37, v17
	v_fma_f32 v17, v224, |v134|, v22
	v_exp_f32_e32 v32, v16
	v_exp_f32_e32 v38, v17
	v_fma_f32 v17, v224, |v135|, v23
	v_add_f32_e32 v16, 0, v32
	v_exp_f32_e32 v23, v17
	v_add_f32_e32 v16, v33, v16
	v_add_f32_e32 v16, v34, v16
	v_fma_f32 v17, v224, |v137|, v24
	v_add_f32_e32 v16, v35, v16
	v_add_f32_e32 v16, v36, v16
	v_exp_f32_e32 v52, v17
	v_add_f32_e32 v16, v37, v16
	v_add_f32_e32 v16, v38, v16
	v_add_f32_e32 v16, v23, v16
	v_add_f32_e32 v60, v52, v16
	v_fma_f32 v16, v224, |v138|, v25
	v_exp_f32_e32 v61, v16
	v_fma_f32 v16, v224, |v139|, v26
	v_exp_f32_e32 v62, v16
	v_fma_f32 v16, v224, |v140|, v27
	v_exp_f32_e32 v63, v16
	v_fma_f32 v16, v224, |v141|, v28
	v_exp_f32_e32 v226, v16
	v_fma_f32 v16, v224, |v142|, v29
	v_exp_f32_e32 v227, v16
	v_fma_f32 v20, v224, |v143|, v30
	ds_read_b64_tr_b16 v[16:17], v200 offset:55296
	ds_read_b64_tr_b16 v[18:19], v200 offset:56832
	ds_read_b64_tr_b16 v[26:27], v200 offset:56896
	ds_read_b64_tr_b16 v[24:25], v200 offset:55360
	v_exp_f32_e32 v228, v20
	v_cvt_pk_bf16_f32 v20, v32, v33
	v_cvt_pk_bf16_f32 v21, v34, v35
	v_cvt_pk_bf16_f32 v22, v36, v37
	v_cvt_pk_bf16_f32 v23, v38, v23
	s_waitcnt lgkmcnt(2)
	s_nop 0
	v_mfma_f32_32x32x16_bf16 v[32:47], v[16:19], v[20:23], 0
	v_fma_f32 v16, v224, |v243|, v31
	v_mov_b32_e32 v53, v16
	ds_read_b64_tr_b16 v[48:49], v200 offset:58368
	ds_read_b64_tr_b16 v[50:51], v200 offset:59904
	v_exp_f32_e32 v229, v53
	ds_read_b64_tr_b16 v[58:59], v200 offset:59968
	ds_read_b64_tr_b16 v[56:57], v200 offset:58432
	v_cvt_pk_bf16_f32 v52, v52, v61
	s_waitcnt lgkmcnt(4)
	v_mfma_f32_32x32x16_bf16 v[16:31], v[24:27], v[20:23], 0
	v_cvt_pk_bf16_f32 v53, v62, v63
	v_cvt_pk_bf16_f32 v54, v226, v227
	v_cvt_pk_bf16_f32 v55, v228, v229
	s_waitcnt lgkmcnt(2)
	s_nop 0
	v_mfma_f32_32x32x16_bf16 v[32:47], v[48:51], v[52:55], v[32:47]
	v_add_f32_e32 v48, v61, v60
	v_add_f32_e32 v48, v62, v48
	v_add_f32_e32 v48, v63, v48
	v_add_f32_e32 v48, v226, v48
	v_add_f32_e32 v48, v227, v48
	v_add_f32_e32 v48, v228, v48
	v_add_f32_e32 v48, v229, v48
	s_waitcnt lgkmcnt(0)
	v_mfma_f32_32x32x16_bf16 v[16:31], v[56:59], v[52:55], v[16:31]
	v_add_f32_e32 v238, 0, v48
	s_branch .Lattn1_t1
